# v76 + DPP inclusive scan for the wave-0 decay prefix (replaces 7 bpermute round trips per chunk)
# speedup vs baseline: 1.0128x; 1.0017x over previous
.LBB0_779:
	s_or_b64 exec, exec, s[0:1]
	v_pk_mul_f32 v[18:19], v[146:147], v[50:51]
	s_lshl_b32 s0, s35, 11
	s_and_b32 s0, s0, 0x800
	s_add_i32 s0, s0, 0
	v_sub_f32_e32 v19, v18, v19
	v_lshl_add_u32 v21, v16, 3, s0
	v_add_u32_e32 v24, 0x22000, v21
	v_mov_b32_e32 v17, v19
	s_nop 1
	v_add_f32_dpp v17, v17, v17 row_shr:1 row_mask:0xf bank_mask:0xf bound_ctrl:0
	s_nop 1
	v_add_f32_dpp v17, v17, v17 row_shr:2 row_mask:0xf bank_mask:0xf bound_ctrl:0
	s_nop 1
	v_add_f32_dpp v17, v17, v17 row_shr:4 row_mask:0xf bank_mask:0xf bound_ctrl:0
	s_nop 1
	v_add_f32_dpp v17, v17, v17 row_shr:8 row_mask:0xf bank_mask:0xf bound_ctrl:0
	s_nop 1
	v_add_f32_dpp v17, v17, v17 row_bcast:15 row_mask:0xa bank_mask:0xf
	s_nop 1
	v_add_f32_dpp v17, v17, v17 row_bcast:31 row_mask:0xc bank_mask:0xf
	s_nop 1
	v_readlane_b32 s100, v17, 63
	s_nop 3
	v_mov_b32_e32 v22, s100
	v_sub_f32_e32 v16, v17, v19
	v_add_f32_e32 v16, v18, v16
	v_mov_b32_e32 v18, v146
	s_waitcnt lgkmcnt(0)
	v_sub_f32_e32 v19, v22, v16
	v_mul_f32_e32 v19, 0x3fb8aa3b, v19
	v_exp_f32_e32 v20, v19
	v_sub_f32_e32 v19, v22, v17
	v_mul_f32_e32 v19, 0x3fb8aa3b, v19
	v_exp_f32_e32 v21, v19
	v_mul_f32_e32 v19, 0x3fb8aa3b, v16
	v_exp_f32_e32 v22, v19
	v_mul_f32_e32 v19, 0x3fb8aa3b, v17
	v_exp_f32_e32 v23, v19
	v_mov_b32_e32 v19, v51
	ds_write2st64_b64 v24, v[16:17], v[18:19] offset1:1
	v_pk_mul_f32 v[16:17], v[18:19], v[20:21]
	ds_write2st64_b64 v24, v[16:17], v[22:23] offset0:2 offset1:3
